# attention: each MFMA segment's 10 LDS fragment reads issued at the tail of the preceding softmax segment (before the barrier), single lgkmcnt(0) at the MFMA segment head
# baseline (speedup 1.0000x reference)
; #define AT_BAR() do { __builtin_amdgcn_sched_barrier(0); asm volatile("s_waitcnt lgkmcnt(0)\n\ts_barrier" ::: "memory"); __builtin_amdgcn_sched_barrier(0); } while (0)
; #define AT_PIN_M() asm volatile("" : "+v"(p[0]), "+v"(p[1]), "+v"(o[0][0]), "+v"(o[0][1]), "+v"(o[1][0]), "+v"(o[1][1]))
; __device__ __forceinline__ void attn_phase(LAS unsigned char* lds, const bf16_t* Qb, const bf16_t* Kimg, const bf16_t* Vimg, bf16_t* AB, int bid, int G, int wave_k) {
;     ...
;         int b_prev = 2 * AT_BUF, b_cur = 0, b_next = AT_BUF;
;         AT_ISSUE(0, 0); AT_ISSUE(1, AT_BUF);
;         asm volatile("s_waitcnt vmcnt(0)" ::: "memory"); AT_BAR();
;         if (grpB) AT_BAR();
;         for (int t = 0; t < 256; ++t) {
;             AT_MSEG(b_cur, 0, (t > 0 ? b_prev : b_cur), 2);
;             AT_PIN_M();
;             AT_BAR();
;             AT_SM(t == 0);
.LBB0_962:
	s_waitcnt lgkmcnt(0)
	s_barrier
	s_add_u32 s0, s0, 0x6000
	s_addc_u32 s1, s1, 0
	s_mul_i32 s16, s55, 3
	s_add_u32 s18, s18, s16
	s_addc_u32 s19, s19, 0
	s_add_u32 s20, s20, 0x9000
	s_addc_u32 s21, s21, 0
	s_mov_b32 s61, 1
	s_mov_b32 s63, 0xa000
	s_movk_i32 s62, 0x5000
	s_mov_b32 s16, 0
	v_mov_b32_e32 v65, v64
	v_mov_b32_e32 v66, v64
	v_mov_b32_e32 v67, v64
	v_mov_b32_e32 v68, v64
	v_mov_b32_e32 v69, v64
	v_mov_b32_e32 v70, v64
	v_mov_b32_e32 v71, v64
	v_mov_b32_e32 v72, v64
	v_mov_b32_e32 v73, v64
	v_mov_b32_e32 v74, v64
	v_mov_b32_e32 v75, v64
	v_mov_b32_e32 v76, v64
	v_mov_b32_e32 v77, v64
	v_mov_b32_e32 v78, v64
	v_mov_b32_e32 v79, v64
	v_mov_b32_e32 v234, v223
	v_mov_b32_e32 v237, v222
	s_mov_b32 s64, s16
	v_add_u32_e32 v160, s62, v236
	v_add_u32_e32 v128, s64, v236
	ds_read_b128 v[104:107], v160
	ds_read_b128 v[108:111], v160 offset:2048
	ds_read_b128 v[120:123], v160 offset:4096
	ds_read_b128 v[124:127], v160 offset:6144
	ds_read_b128 v[210:213], v160 offset:8192
	ds_read_b128 v[230:233], v160 offset:10240
	ds_read_b128 v[238:241], v128 offset:16384
	ds_read_b128 v[242:245], v128 offset:16896
	ds_read_b128 v[246:249], v128 offset:18432
	ds_read_b128 v[250:253], v128 offset:18944
.LBB0_963:
	s_setprio 1
	s_waitcnt lgkmcnt(0)
	v_mfma_f32_32x32x16_bf16 v[144:159], v[104:107], v[162:165], v[64:79]
	v_mfma_f32_32x32x16_bf16 v[128:143], v[104:107], v[186:189], v[80:95]
	v_mfma_f32_32x32x16_bf16 v[144:159], v[108:111], v[166:169], v[144:159]
	v_mfma_f32_32x32x16_bf16 v[128:143], v[108:111], v[190:193], v[128:143]
	v_mfma_f32_32x32x16_bf16 v[144:159], v[120:123], v[170:173], v[144:159]
	v_mfma_f32_32x32x16_bf16 v[128:143], v[120:123], v[194:197], v[128:143]
	v_mfma_f32_32x32x16_bf16 v[144:159], v[124:127], v[174:177], v[144:159]
	v_mfma_f32_32x32x16_bf16 v[128:143], v[124:127], v[198:201], v[128:143]
	v_mfma_f32_32x32x16_bf16 v[144:159], v[210:213], v[178:181], v[144:159]
	v_mfma_f32_32x32x16_bf16 v[128:143], v[210:213], v[202:205], v[128:143]
	v_mfma_f32_32x32x16_bf16 v[144:159], v[230:233], v[182:185], v[144:159]
	v_mfma_f32_32x32x16_bf16 v[128:143], v[230:233], v[206:209], v[128:143]
	v_mfma_f32_32x32x16_bf16 v[48:63], v[238:241], v[116:119], v[48:63]
	v_mfma_f32_32x32x16_bf16 v[32:47], v[242:245], v[116:119], v[32:47]
	v_mfma_f32_32x32x16_bf16 v[16:31], v[238:241], v[100:103], v[16:31]
	v_mfma_f32_32x32x16_bf16 v[0:15], v[242:245], v[100:103], v[0:15]
	v_mfma_f32_32x32x16_bf16 v[48:63], v[246:249], v[112:115], v[48:63]
	v_mfma_f32_32x32x16_bf16 v[32:47], v[250:253], v[112:115], v[32:47]
	v_mfma_f32_32x32x16_bf16 v[16:31], v[246:249], v[96:99], v[16:31]
	v_mfma_f32_32x32x16_bf16 v[0:15], v[250:253], v[96:99], v[0:15]
	s_setprio 0
	s_barrier
	s_nop 1
	v_exp_f32_e32 v144, v144
	v_exp_f32_e32 v145, v145
	v_exp_f32_e32 v146, v146
	v_exp_f32_e32 v147, v147
	v_add_f32_e32 v210, v144, v145
	v_exp_f32_e32 v148, v148
	v_add_f32_e32 v210, v210, v146
	v_exp_f32_e32 v149, v149
	v_add_f32_e32 v210, v210, v147
	v_exp_f32_e32 v150, v150
	v_add_f32_e32 v210, v210, v148
	v_exp_f32_e32 v151, v151
	v_add_f32_e32 v210, v210, v149
	v_exp_f32_e32 v152, v152
	v_add_f32_e32 v210, v210, v150
	v_exp_f32_e32 v153, v153
	v_add_f32_e32 v210, v210, v151
	v_exp_f32_e32 v154, v154
	v_add_f32_e32 v210, v210, v152
	v_exp_f32_e32 v155, v155
	v_add_f32_e32 v210, v210, v153
	v_exp_f32_e32 v156, v156
	v_add_f32_e32 v210, v210, v154
	v_exp_f32_e32 v157, v157
	v_add_f32_e32 v210, v210, v155
	v_exp_f32_e32 v158, v158
	v_add_f32_e32 v210, v210, v156
	v_exp_f32_e32 v159, v159
	v_add_f32_e32 v210, v210, v157
	v_add_f32_e32 v210, v210, v158
	v_add_f32_e32 v210, v210, v159
	v_exp_f32_e32 v128, v128
	v_exp_f32_e32 v129, v129
	v_exp_f32_e32 v130, v130
	v_exp_f32_e32 v131, v131
	v_add_f32_e32 v211, v128, v129
	v_exp_f32_e32 v132, v132
	v_add_f32_e32 v211, v211, v130
	v_exp_f32_e32 v133, v133
	v_add_f32_e32 v211, v211, v131
	v_exp_f32_e32 v134, v134
	v_add_f32_e32 v211, v211, v132
	v_exp_f32_e32 v135, v135
	v_add_f32_e32 v211, v211, v133
	v_exp_f32_e32 v136, v136
	v_add_f32_e32 v211, v211, v134
	v_exp_f32_e32 v137, v137
	v_add_f32_e32 v211, v211, v135
	v_exp_f32_e32 v138, v138
	v_add_f32_e32 v211, v211, v136
	v_exp_f32_e32 v139, v139
	v_add_f32_e32 v211, v211, v137
	v_exp_f32_e32 v140, v140
	v_add_f32_e32 v211, v211, v138
	v_exp_f32_e32 v141, v141
	v_add_f32_e32 v211, v211, v139
	v_exp_f32_e32 v142, v142
	v_add_f32_e32 v211, v211, v140
	v_exp_f32_e32 v143, v143
	v_add_f32_e32 v211, v211, v141
	v_add_f32_e32 v211, v211, v142
	v_add_f32_e32 v211, v211, v143
	v_max_f32_e32 v212, v210, v211
	v_cmp_lt_f32_e32 vcc, 0x43800000, v212
	s_cbranch_vccnz .Lph_rare_a
; __device__ __forceinline__ void attn_phase(LAS unsigned char* lds, const bf16_t* Qb, const bf16_t* Kimg, const bf16_t* Vimg, bf16_t* AB, int bid, int G, int wave_k) {
;     ...
;             const bool issued = (t + 2 < 256);
;             if (issued) AT_ISSUE(t + 2, b_prev);
;             AT_MSEG(b_cur, 1, b_cur, 0);
.Lph_cont_a:
	v_add_f32_e32 v234, v234, v210
	v_add_f32_e32 v237, v237, v211
	v_cvt_pk_bf16_f32 v151, v150, v151
	v_cvt_pk_bf16_f32 v150, v148, v149
	v_cvt_pk_bf16_f32 v149, v146, v147
	v_cvt_pk_bf16_f32 v148, v144, v145
	v_cvt_pk_bf16_f32 v144, v152, v153
	v_cvt_pk_bf16_f32 v145, v154, v155
	v_cvt_pk_bf16_f32 v146, v156, v157
	v_cvt_pk_bf16_f32 v147, v158, v159
	v_cvt_pk_bf16_f32 v135, v134, v135
	v_cvt_pk_bf16_f32 v134, v132, v133
	v_cvt_pk_bf16_f32 v133, v130, v131
	v_cvt_pk_bf16_f32 v132, v128, v129
	v_cvt_pk_bf16_f32 v128, v136, v137
	v_cvt_pk_bf16_f32 v129, v138, v139
	v_cvt_pk_bf16_f32 v130, v140, v141
	v_cvt_pk_bf16_f32 v131, v142, v143
	ds_read_b128 v[136:139], v160 offset:512
	ds_read_b128 v[140:143], v160 offset:2560
	ds_read_b128 v[154:157], v160 offset:4608
	ds_read_b128 v[210:213], v160 offset:6656
	ds_read_b128 v[222:225], v160 offset:8704
	ds_read_b128 v[230:233], v160 offset:10752
	ds_read_b128 v[238:241], v160 offset:12288
	ds_read_b128 v[242:245], v160 offset:12800
	ds_read_b128 v[246:249], v160 offset:14336
	ds_read_b128 v[250:253], v160 offset:14848
	s_waitcnt vmcnt(0)
	s_barrier
	s_cmpk_gt_u32 s61, 0xfd
	s_cbranch_scc1 .LBB0_969
	s_add_i32 m0, s54, s64
	s_bitcmp1_b32 s42, 0
	global_load_lds_dwordx4 v218, s[20:21]
	s_add_i32 m0, m0, 0x2000
	s_add_u32 s20, s20, 0x3000
	s_addc_u32 s21, s21, 0
	global_load_lds_dwordx4 v218, s[18:19]
	s_add_u32 s18, s18, s55
	s_addc_u32 s19, s19, 0
	s_bitcmp1_b32 s42, 0
	s_cbranch_scc1 .LBB0_969
	s_add_i32 m0, m0, 0x2000
	s_nop 0
	global_load_lds_dwordx4 v218, s[0:1]
	s_add_u32 s0, s0, 0x2000
	s_addc_u32 s1, s1, 0
.LBB0_969:
	s_setprio 1
	s_waitcnt lgkmcnt(0)
	v_mfma_f32_32x32x16_bf16 v[112:127], v[136:139], v[162:165], v[64:79]
	v_mfma_f32_32x32x16_bf16 v[96:111], v[136:139], v[186:189], v[80:95]
	v_mfma_f32_32x32x16_bf16 v[112:127], v[140:143], v[166:169], v[112:127]
	v_mfma_f32_32x32x16_bf16 v[96:111], v[140:143], v[190:193], v[96:111]
	v_mfma_f32_32x32x16_bf16 v[112:127], v[154:157], v[170:173], v[112:127]
	v_mfma_f32_32x32x16_bf16 v[96:111], v[154:157], v[194:197], v[96:111]
	v_mfma_f32_32x32x16_bf16 v[112:127], v[210:213], v[174:177], v[112:127]
	v_mfma_f32_32x32x16_bf16 v[96:111], v[210:213], v[198:201], v[96:111]
	v_mfma_f32_32x32x16_bf16 v[112:127], v[222:225], v[178:181], v[112:127]
	v_mfma_f32_32x32x16_bf16 v[96:111], v[222:225], v[202:205], v[96:111]
	v_mfma_f32_32x32x16_bf16 v[112:127], v[230:233], v[182:185], v[112:127]
	v_mfma_f32_32x32x16_bf16 v[96:111], v[230:233], v[206:209], v[96:111]
	v_mfma_f32_32x32x16_bf16 v[48:63], v[238:241], v[148:151], v[48:63]
	v_mfma_f32_32x32x16_bf16 v[32:47], v[242:245], v[148:151], v[32:47]
	v_mfma_f32_32x32x16_bf16 v[16:31], v[238:241], v[132:135], v[16:31]
	v_mfma_f32_32x32x16_bf16 v[0:15], v[242:245], v[132:135], v[0:15]
	v_mfma_f32_32x32x16_bf16 v[48:63], v[246:249], v[144:147], v[48:63]
	v_mfma_f32_32x32x16_bf16 v[32:47], v[250:253], v[144:147], v[32:47]
	v_mfma_f32_32x32x16_bf16 v[16:31], v[246:249], v[128:131], v[16:31]
	v_mfma_f32_32x32x16_bf16 v[0:15], v[250:253], v[128:131], v[0:15]
	s_setprio 0

; __device__ __forceinline__ void attn_phase(LAS unsigned char* lds, const bf16_t* Qb, const bf16_t* Kimg, const bf16_t* Vimg, bf16_t* AB, int bid, int G, int wave_k) {
;     ...
;             AT_MSEG(b_cur, 0, (t > 0 ? b_prev : b_cur), 2);
.Lph_cont_b:
	v_add_f32_e32 v234, v234, v210
	v_add_f32_e32 v237, v237, v211
	v_cvt_pk_bf16_f32 v119, v118, v119
	v_cvt_pk_bf16_f32 v118, v116, v117
	v_cvt_pk_bf16_f32 v117, v114, v115
	v_cvt_pk_bf16_f32 v116, v112, v113
	v_cvt_pk_bf16_f32 v112, v120, v121
	v_cvt_pk_bf16_f32 v113, v122, v123
	v_cvt_pk_bf16_f32 v114, v124, v125
	v_cvt_pk_bf16_f32 v115, v126, v127
	v_cvt_pk_bf16_f32 v103, v102, v103
	v_cvt_pk_bf16_f32 v102, v100, v101
	v_cvt_pk_bf16_f32 v101, v98, v99
	v_cvt_pk_bf16_f32 v100, v96, v97
	v_cvt_pk_bf16_f32 v96, v104, v105
	v_cvt_pk_bf16_f32 v97, v106, v107
	v_cvt_pk_bf16_f32 v98, v108, v109
	v_cvt_pk_bf16_f32 v99, v110, v111
	ds_read_b128 v[104:107], v160
	ds_read_b128 v[108:111], v160 offset:2048
	ds_read_b128 v[120:123], v160 offset:4096
	ds_read_b128 v[124:127], v160 offset:6144
	ds_read_b128 v[210:213], v160 offset:8192
	ds_read_b128 v[230:233], v160 offset:10240
	ds_read_b128 v[238:241], v128 offset:16384
	ds_read_b128 v[242:245], v128 offset:16896
	ds_read_b128 v[246:249], v128 offset:18432
	ds_read_b128 v[250:253], v128 offset:18944
